# early-arrive barrier: each GEMM MFMA segment's closing s_barrier moved up by 4 MFMAs so the computing half's tail MFMAs cover the partner half's wake-up
# baseline (speedup 1.0000x reference)
; #define PG8_STAGE(bufoff, gbase, voff) do { _Pragma("unroll") for (int _i = 0; _i < 2; ++_i) \
;         __builtin_amdgcn_global_load_lds((const unsigned*)((const char*)(gbase) + (voff)[_i]), (PG8_LAS unsigned*)(lds + (bufoff) + ldsw + _i * 8192), 16, 0, 0); } while (0)
; #define PG8_LDA(dst, b, h) do { _Pragma("unroll") for (int m = 0; m < 4; ++m) _Pragma("unroll") for (int k = 0; k < 2; ++k) dst[m][k] = *(const PG8_LAS bf16x8*)(lds + PG8_SA(b, h) + aoff + m * 2048 + k * 1024); } while (0)
; #define PG8_LDB(dst, b, h) do { _Pragma("unroll") for (int n = 0; n < 2; ++n) _Pragma("unroll") for (int k = 0; k < 2; ++k) dst[n][k] = *(const PG8_LAS bf16x8*)(lds + PG8_SB(b, h) + boff + n * 2048 + k * 1024); } while (0)
; #define PG8_MMA(ai, bj, At, Bt) do { __builtin_amdgcn_s_setprio(1); _Pragma("unroll") for (int m = 0; m < 4; ++m) _Pragma("unroll") for (int n = 0; n < 2; ++n) _Pragma("unroll") for (int k = 0; k < 2; ++k) \
;         acc[ai][bj][m][n] = __builtin_amdgcn_mfma_f32_16x16x32_bf16(Bt[n][k], At[m][k], acc[ai][bj][m][n], 0, 0, 0); __builtin_amdgcn_s_setprio(0); } while (0)
; #define PG8_WAIT_V(n) asm volatile("s_waitcnt vmcnt(" #n ")" ::: "memory")
; #define PG8_WAIT_L(n) asm volatile("s_waitcnt lgkmcnt(" #n ")" ::: "memory")
; #define PG8_BAR __builtin_amdgcn_s_barrier()
; #define PG8_SCHED __builtin_amdgcn_sched_barrier(0)
; template <class Epi, class Sched, bool ALIGN_EPI = false, bool SP2 = false>
; __device__ __forceinline__ void gemm_phase(PG8_LAS unsigned char* lds, const Gemm g, const Sched& S, const Epi& E) {
;     ...
;             PG8_LDB(B0, 0, 0); PG8_LDB(B1, 0, 1); PG8_SCHED; PG8_LDA(At, 0, 0); PG8_STAGE(PG8_SA(1, 1), a1 + hstep, voffA);
;             PG8_WAIT_V(8); PG8_WAIT_L(0); PG8_BAR; PG8_MMA(0, 0, At, B0); PG8_MMA(0, 1, At, B1); PG8_BAR; PG8_SCHED;
;             PG8_LDA(At, 0, 1); PG8_STAGE(PG8_SB(0, 0), b2, voffB); PG8_STAGE(PG8_SB(0, 1), b2 + hstep, voffB); PG8_STAGE(PG8_SA(0, 0), a2, voffA);
;             PG8_WAIT_V(8); PG8_WAIT_L(0); PG8_BAR; PG8_MMA(1, 0, At, B0); PG8_MMA(1, 1, At, B1); PG8_BAR; PG8_SCHED;
.LBB0_417:
	s_add_u32 s0, s40, 0xfff80080
	s_addc_u32 s1, s41, -1
	s_add_i32 s30, 0, 0x10000
	s_cmp_eq_u32 s19, 28
	s_cselect_b32 s5, s7, s1
	s_cselect_b32 s4, s8, s0
	s_cselect_b32 s1, s9, s17
	s_cselect_b32 s0, s14, s15
	s_add_i32 s33, 0, 0x14000
	v_add_u32_e32 v142, s30, v203
	v_add_u32_e32 v158, s33, v203
	ds_read_b128 v[130:133], v142
	ds_read_b128 v[134:137], v142 offset:1024
	ds_read_b128 v[138:141], v142 offset:2048
	ds_read_b128 v[142:145], v142 offset:3072
	ds_read_b128 v[146:149], v158
	ds_read_b128 v[150:153], v158 offset:1024
	ds_read_b128 v[154:157], v158 offset:2048
	ds_read_b128 v[158:161], v158 offset:3072
	v_lshl_add_u64 v[190:191], s[40:41], 0, v[188:189]
	s_add_i32 m0, s67, 0xc000
	ds_read_b128 v[162:165], v209
	ds_read_b128 v[166:169], v209 offset:1024
	ds_read_b128 v[170:173], v209 offset:2048
	ds_read_b128 v[174:177], v209 offset:3072
	ds_read_b128 v[210:213], v209 offset:4096
	ds_read_b128 v[232:235], v209 offset:5120
	ds_read_b128 v[242:245], v209 offset:6144
	ds_read_b128 v[246:249], v209 offset:7168
	global_load_lds_dwordx4 v[190:191], off
	v_lshl_add_u64 v[190:191], s[40:41], 0, v[186:187]
	s_add_i32 m0, s67, 0xe000
	s_nop 0
	global_load_lds_dwordx4 v[190:191], off
	s_waitcnt vmcnt(8)
	s_waitcnt lgkmcnt(0)
	s_barrier
	v_mfma_f32_16x16x32_bf16 v[126:129], v[130:133], v[162:165], v[126:129]
	v_mfma_f32_16x16x32_bf16 v[122:125], v[138:141], v[162:165], v[122:125]
	v_mfma_f32_16x16x32_bf16 v[110:113], v[130:133], v[170:173], v[110:113]
	v_mfma_f32_16x16x32_bf16 v[106:109], v[138:141], v[170:173], v[106:109]
	v_mfma_f32_16x16x32_bf16 v[92:95], v[130:133], v[210:213], v[92:95]
	v_mfma_f32_16x16x32_bf16 v[88:91], v[138:141], v[210:213], v[88:91]
	v_mfma_f32_16x16x32_bf16 v[76:79], v[130:133], v[242:245], v[76:79]
	v_mfma_f32_16x16x32_bf16 v[72:75], v[138:141], v[242:245], v[72:75]
	v_mfma_f32_16x16x32_bf16 v[126:129], v[134:137], v[166:169], v[126:129]
	v_mfma_f32_16x16x32_bf16 v[122:125], v[142:145], v[166:169], v[122:125]
	v_mfma_f32_16x16x32_bf16 v[110:113], v[134:137], v[174:177], v[110:113]
	v_mfma_f32_16x16x32_bf16 v[106:109], v[142:145], v[174:177], v[106:109]
	v_mfma_f32_16x16x32_bf16 v[92:95], v[134:137], v[232:235], v[92:95]
	v_mfma_f32_16x16x32_bf16 v[88:91], v[142:145], v[232:235], v[88:91]
	v_mfma_f32_16x16x32_bf16 v[76:79], v[134:137], v[246:249], v[76:79]
	v_mfma_f32_16x16x32_bf16 v[72:75], v[142:145], v[246:249], v[72:75]
	v_mfma_f32_16x16x32_bf16 v[118:121], v[146:149], v[162:165], v[118:121]
	v_mfma_f32_16x16x32_bf16 v[114:117], v[154:157], v[162:165], v[114:117]
	v_mfma_f32_16x16x32_bf16 v[102:105], v[146:149], v[170:173], v[102:105]
	v_mfma_f32_16x16x32_bf16 v[98:101], v[154:157], v[170:173], v[98:101]
	v_mfma_f32_16x16x32_bf16 v[84:87], v[146:149], v[210:213], v[84:87]
	v_mfma_f32_16x16x32_bf16 v[80:83], v[154:157], v[210:213], v[80:83]
	v_mfma_f32_16x16x32_bf16 v[68:71], v[146:149], v[242:245], v[68:71]
	v_mfma_f32_16x16x32_bf16 v[64:67], v[154:157], v[242:245], v[64:67]
	v_mfma_f32_16x16x32_bf16 v[118:121], v[150:153], v[166:169], v[118:121]
	v_mfma_f32_16x16x32_bf16 v[114:117], v[158:161], v[166:169], v[114:117]
	v_mfma_f32_16x16x32_bf16 v[102:105], v[150:153], v[174:177], v[102:105]
	v_mfma_f32_16x16x32_bf16 v[98:101], v[158:161], v[174:177], v[98:101]
	s_barrier
	v_mfma_f32_16x16x32_bf16 v[84:87], v[150:153], v[232:235], v[84:87]
	v_mfma_f32_16x16x32_bf16 v[80:83], v[158:161], v[232:235], v[80:83]
	v_mfma_f32_16x16x32_bf16 v[68:71], v[150:153], v[246:249], v[68:71]
	v_mfma_f32_16x16x32_bf16 v[64:67], v[158:161], v[246:249], v[64:67]
	s_add_i32 s30, s30, s28
	v_lshl_add_u64 v[190:191], s[0:1], 0, v[96:97]
	s_mov_b32 m0, s30
	ds_read_b128 v[162:165], v209 offset:16384
	ds_read_b128 v[166:169], v209 offset:17408
	ds_read_b128 v[170:173], v209 offset:18432
	ds_read_b128 v[174:177], v209 offset:19456
	ds_read_b128 v[210:213], v209 offset:20480
	ds_read_b128 v[232:235], v209 offset:21504
	ds_read_b128 v[242:245], v209 offset:22528
	ds_read_b128 v[246:249], v209 offset:23552
	global_load_lds_dwordx4 v[190:191], off
	s_add_i32 m0, s30, 0x2000
	s_add_u32 s30, s0, 0x80000
	v_lshl_add_u64 v[204:205], s[0:1], 0, v[178:179]
	s_addc_u32 s31, s1, 0
	s_add_i32 s33, s33, s28
	global_load_lds_dwordx4 v[204:205], off
	v_lshl_add_u64 v[214:215], s[30:31], 0, v[96:97]
	s_mov_b32 m0, s33
	v_lshl_add_u64 v[228:229], s[4:5], 0, v[180:181]
	global_load_lds_dwordx4 v[214:215], off
	v_lshl_add_u64 v[214:215], s[30:31], 0, v[178:179]
	s_add_i32 m0, s33, 0x2000
	s_nop 0
	global_load_lds_dwordx4 v[214:215], off
	v_lshl_add_u64 v[214:215], s[4:5], 0, v[182:183]
	s_mov_b32 m0, s67
	s_nop 0
	global_load_lds_dwordx4 v[214:215], off
	s_mov_b32 m0, s68
	s_nop 0
	global_load_lds_dwordx4 v[228:229], off
	s_waitcnt vmcnt(8)
	s_waitcnt lgkmcnt(0)
	s_barrier
; #define PG8_STAGE(bufoff, gbase, voff) do { _Pragma("unroll") for (int _i = 0; _i < 2; ++_i) \
;         __builtin_amdgcn_global_load_lds((const unsigned*)((const char*)(gbase) + (voff)[_i]), (PG8_LAS unsigned*)(lds + (bufoff) + ldsw + _i * 8192), 16, 0, 0); } while (0)
; #define PG8_LDA(dst, b, h) do { _Pragma("unroll") for (int m = 0; m < 4; ++m) _Pragma("unroll") for (int k = 0; k < 2; ++k) dst[m][k] = *(const PG8_LAS bf16x8*)(lds + PG8_SA(b, h) + aoff + m * 2048 + k * 1024); } while (0)
; #define PG8_LDB(dst, b, h) do { _Pragma("unroll") for (int n = 0; n < 2; ++n) _Pragma("unroll") for (int k = 0; k < 2; ++k) dst[n][k] = *(const PG8_LAS bf16x8*)(lds + PG8_SB(b, h) + boff + n * 2048 + k * 1024); } while (0)
; #define PG8_MMA(ai, bj, At, Bt) do { __builtin_amdgcn_s_setprio(1); _Pragma("unroll") for (int m = 0; m < 4; ++m) _Pragma("unroll") for (int n = 0; n < 2; ++n) _Pragma("unroll") for (int k = 0; k < 2; ++k) \
;         acc[ai][bj][m][n] = __builtin_amdgcn_mfma_f32_16x16x32_bf16(Bt[n][k], At[m][k], acc[ai][bj][m][n], 0, 0, 0); __builtin_amdgcn_s_setprio(0); } while (0)
; #define PG8_WAIT_V(n) asm volatile("s_waitcnt vmcnt(" #n ")" ::: "memory")
; #define PG8_WAIT_L(n) asm volatile("s_waitcnt lgkmcnt(" #n ")" ::: "memory")
; #define PG8_BAR __builtin_amdgcn_s_barrier()
; #define PG8_SCHED __builtin_amdgcn_sched_barrier(0)
; template <class Epi, class Sched, bool ALIGN_EPI = false, bool SP2 = false>
; __device__ __forceinline__ void gemm_phase(PG8_LAS unsigned char* lds, const Gemm g, const Sched& S, const Epi& E) {
;     ...
;             PG8_WAIT_V(8); PG8_WAIT_L(0); PG8_BAR; PG8_MMA(1, 0, At, B0); PG8_MMA(1, 1, At, B1); PG8_BAR; PG8_SCHED;
;             PG8_LDB(B0, 1, 0); PG8_LDB(B1, 1, 1); PG8_SCHED; PG8_LDA(At, 1, 0); PG8_STAGE(PG8_SA(0, 1), a2 + hstep, voffA);
;             PG8_WAIT_V(8); PG8_WAIT_L(0); PG8_BAR; PG8_MMA(0, 0, At, B0); PG8_MMA(0, 1, At, B1); PG8_BAR; PG8_SCHED;
	v_mfma_f32_16x16x32_bf16 v[60:63], v[130:133], v[162:165], v[60:63]
	v_mfma_f32_16x16x32_bf16 v[56:59], v[138:141], v[162:165], v[56:59]
	v_mfma_f32_16x16x32_bf16 v[44:47], v[130:133], v[170:173], v[44:47]
	v_mfma_f32_16x16x32_bf16 v[40:43], v[138:141], v[170:173], v[40:43]
	v_mfma_f32_16x16x32_bf16 v[28:31], v[130:133], v[210:213], v[28:31]
	v_mfma_f32_16x16x32_bf16 v[24:27], v[138:141], v[210:213], v[24:27]
	v_mfma_f32_16x16x32_bf16 v[12:15], v[130:133], v[242:245], v[12:15]
	v_mfma_f32_16x16x32_bf16 v[8:11], v[138:141], v[242:245], v[8:11]
	v_mfma_f32_16x16x32_bf16 v[60:63], v[134:137], v[166:169], v[60:63]
	v_mfma_f32_16x16x32_bf16 v[56:59], v[142:145], v[166:169], v[56:59]
	v_mfma_f32_16x16x32_bf16 v[44:47], v[134:137], v[174:177], v[44:47]
	v_mfma_f32_16x16x32_bf16 v[40:43], v[142:145], v[174:177], v[40:43]
	v_mfma_f32_16x16x32_bf16 v[28:31], v[134:137], v[232:235], v[28:31]
	v_mfma_f32_16x16x32_bf16 v[24:27], v[142:145], v[232:235], v[24:27]
	v_mfma_f32_16x16x32_bf16 v[12:15], v[134:137], v[246:249], v[12:15]
	v_mfma_f32_16x16x32_bf16 v[8:11], v[142:145], v[246:249], v[8:11]
	v_mfma_f32_16x16x32_bf16 v[52:55], v[146:149], v[162:165], v[52:55]
	v_mfma_f32_16x16x32_bf16 v[48:51], v[154:157], v[162:165], v[48:51]
	v_mfma_f32_16x16x32_bf16 v[36:39], v[146:149], v[170:173], v[36:39]
	v_mfma_f32_16x16x32_bf16 v[32:35], v[154:157], v[170:173], v[32:35]
	v_mfma_f32_16x16x32_bf16 v[20:23], v[146:149], v[210:213], v[20:23]
	v_mfma_f32_16x16x32_bf16 v[16:19], v[154:157], v[210:213], v[16:19]
	v_mfma_f32_16x16x32_bf16 v[4:7], v[146:149], v[242:245], v[4:7]
	v_mfma_f32_16x16x32_bf16 v[0:3], v[154:157], v[242:245], v[0:3]
	v_mfma_f32_16x16x32_bf16 v[52:55], v[150:153], v[166:169], v[52:55]
	v_mfma_f32_16x16x32_bf16 v[48:51], v[158:161], v[166:169], v[48:51]
	v_mfma_f32_16x16x32_bf16 v[36:39], v[150:153], v[174:177], v[36:39]
	v_mfma_f32_16x16x32_bf16 v[32:35], v[158:161], v[174:177], v[32:35]
	s_barrier
	v_mfma_f32_16x16x32_bf16 v[20:23], v[150:153], v[232:235], v[20:23]
	v_mfma_f32_16x16x32_bf16 v[16:19], v[158:161], v[232:235], v[16:19]
	v_mfma_f32_16x16x32_bf16 v[4:7], v[150:153], v[246:249], v[4:7]
	v_mfma_f32_16x16x32_bf16 v[0:3], v[158:161], v[246:249], v[0:3]
	s_add_i32 s30, 0, 0x18000
	s_add_i32 s31, 0, 0x1c000
	v_add_u32_e32 v142, s30, v203
	v_add_u32_e32 v158, s31, v203
	ds_read_b128 v[130:133], v142
	ds_read_b128 v[134:137], v142 offset:1024
	ds_read_b128 v[138:141], v142 offset:2048
	ds_read_b128 v[142:145], v142 offset:3072
	ds_read_b128 v[146:149], v158
	ds_read_b128 v[150:153], v158 offset:1024
	ds_read_b128 v[154:157], v158 offset:2048
	ds_read_b128 v[158:161], v158 offset:3072
	s_add_u32 s4, s4, 0x80000
	s_addc_u32 s5, s5, 0
	s_mov_b32 m0, s69
	v_lshl_add_u64 v[230:231], s[4:5], 0, v[182:183]
	ds_read_b128 v[162:165], v209 offset:32768
	ds_read_b128 v[166:169], v209 offset:33792
	ds_read_b128 v[170:173], v209 offset:34816
	ds_read_b128 v[174:177], v209 offset:35840
	ds_read_b128 v[210:213], v209 offset:36864
	ds_read_b128 v[232:235], v209 offset:37888
	ds_read_b128 v[242:245], v209 offset:38912
	ds_read_b128 v[246:249], v209 offset:39936
	global_load_lds_dwordx4 v[230:231], off
	v_lshl_add_u64 v[230:231], s[4:5], 0, v[180:181]
	s_mov_b32 m0, s72
	s_nop 0
	global_load_lds_dwordx4 v[230:231], off
	s_waitcnt vmcnt(8)
	s_waitcnt lgkmcnt(0)
	s_barrier
	v_mfma_f32_16x16x32_bf16 v[126:129], v[130:133], v[162:165], v[126:129]
	v_mfma_f32_16x16x32_bf16 v[122:125], v[138:141], v[162:165], v[122:125]
	v_mfma_f32_16x16x32_bf16 v[110:113], v[130:133], v[170:173], v[110:113]
	v_mfma_f32_16x16x32_bf16 v[106:109], v[138:141], v[170:173], v[106:109]
	v_mfma_f32_16x16x32_bf16 v[92:95], v[130:133], v[210:213], v[92:95]
	v_mfma_f32_16x16x32_bf16 v[88:91], v[138:141], v[210:213], v[88:91]
	v_mfma_f32_16x16x32_bf16 v[76:79], v[130:133], v[242:245], v[76:79]
	v_mfma_f32_16x16x32_bf16 v[72:75], v[138:141], v[242:245], v[72:75]
	v_mfma_f32_16x16x32_bf16 v[126:129], v[134:137], v[166:169], v[126:129]
	v_mfma_f32_16x16x32_bf16 v[122:125], v[142:145], v[166:169], v[122:125]
	v_mfma_f32_16x16x32_bf16 v[110:113], v[134:137], v[174:177], v[110:113]
	v_mfma_f32_16x16x32_bf16 v[106:109], v[142:145], v[174:177], v[106:109]
	v_mfma_f32_16x16x32_bf16 v[92:95], v[134:137], v[232:235], v[92:95]
	v_mfma_f32_16x16x32_bf16 v[88:91], v[142:145], v[232:235], v[88:91]
	v_mfma_f32_16x16x32_bf16 v[76:79], v[134:137], v[246:249], v[76:79]
	v_mfma_f32_16x16x32_bf16 v[72:75], v[142:145], v[246:249], v[72:75]
	v_mfma_f32_16x16x32_bf16 v[118:121], v[146:149], v[162:165], v[118:121]
	v_mfma_f32_16x16x32_bf16 v[114:117], v[154:157], v[162:165], v[114:117]
	v_mfma_f32_16x16x32_bf16 v[102:105], v[146:149], v[170:173], v[102:105]
	v_mfma_f32_16x16x32_bf16 v[98:101], v[154:157], v[170:173], v[98:101]
	v_mfma_f32_16x16x32_bf16 v[84:87], v[146:149], v[210:213], v[84:87]
	v_mfma_f32_16x16x32_bf16 v[80:83], v[154:157], v[210:213], v[80:83]
	v_mfma_f32_16x16x32_bf16 v[68:71], v[146:149], v[242:245], v[68:71]
	v_mfma_f32_16x16x32_bf16 v[64:67], v[154:157], v[242:245], v[64:67]
	v_mfma_f32_16x16x32_bf16 v[118:121], v[150:153], v[166:169], v[118:121]
	v_mfma_f32_16x16x32_bf16 v[114:117], v[158:161], v[166:169], v[114:117]
	v_mfma_f32_16x16x32_bf16 v[102:105], v[150:153], v[174:177], v[102:105]
	v_mfma_f32_16x16x32_bf16 v[98:101], v[158:161], v[174:177], v[98:101]
	s_barrier
; #define PG8_STAGE(bufoff, gbase, voff) do { _Pragma("unroll") for (int _i = 0; _i < 2; ++_i) \
;         __builtin_amdgcn_global_load_lds((const unsigned*)((const char*)(gbase) + (voff)[_i]), (PG8_LAS unsigned*)(lds + (bufoff) + ldsw + _i * 8192), 16, 0, 0); } while (0)
; #define PG8_LDA(dst, b, h) do { _Pragma("unroll") for (int m = 0; m < 4; ++m) _Pragma("unroll") for (int k = 0; k < 2; ++k) dst[m][k] = *(const PG8_LAS bf16x8*)(lds + PG8_SA(b, h) + aoff + m * 2048 + k * 1024); } while (0)
; #define PG8_MMA(ai, bj, At, Bt) do { __builtin_amdgcn_s_setprio(1); _Pragma("unroll") for (int m = 0; m < 4; ++m) _Pragma("unroll") for (int n = 0; n < 2; ++n) _Pragma("unroll") for (int k = 0; k < 2; ++k) \
;         acc[ai][bj][m][n] = __builtin_amdgcn_mfma_f32_16x16x32_bf16(Bt[n][k], At[m][k], acc[ai][bj][m][n], 0, 0, 0); __builtin_amdgcn_s_setprio(0); } while (0)
; #define PG8_WAIT_V(n) asm volatile("s_waitcnt vmcnt(" #n ")" ::: "memory")
; #define PG8_WAIT_L(n) asm volatile("s_waitcnt lgkmcnt(" #n ")" ::: "memory")
; #define PG8_BAR __builtin_amdgcn_s_barrier()
; #define PG8_SCHED __builtin_amdgcn_sched_barrier(0)
; template <class Epi, class Sched, bool ALIGN_EPI = false, bool SP2 = false>
; __device__ __forceinline__ void gemm_phase(PG8_LAS unsigned char* lds, const Gemm g, const Sched& S, const Epi& E) {
;     ...
;         for (int t = 0; t < nt; t += 2) {
;             const bool last = (t == nt - 2);
;             const char* a1 = cA + (size_t)(t + 1) * kstep;
;             const char* a2 = last ? nA : cA + (size_t)(t + 2) * kstep; const char* b2 = last ? nB : cB + (size_t)(t + 2) * kstep;
;     ...
;             PG8_LDA(At, 1, 1); PG8_STAGE(PG8_SB(1, 0), b3, voffB); PG8_STAGE(PG8_SB(1, 1), b3 + hstep, voffB); PG8_STAGE(PG8_SA(1, 0), a3, voffA);
;             PG8_WAIT_V(8); PG8_WAIT_L(0); PG8_BAR; PG8_MMA(1, 0, At, B0); PG8_MMA(1, 1, At, B1); PG8_BAR; PG8_SCHED;
	v_mfma_f32_16x16x32_bf16 v[84:87], v[150:153], v[232:235], v[84:87]
	v_mfma_f32_16x16x32_bf16 v[80:83], v[158:161], v[232:235], v[80:83]
	v_mfma_f32_16x16x32_bf16 v[68:71], v[150:153], v[246:249], v[68:71]
	v_mfma_f32_16x16x32_bf16 v[64:67], v[158:161], v[246:249], v[64:67]
	s_add_i32 s4, s30, s28
	v_lshl_add_u64 v[190:191], v[190:191], 0, s[20:21]
	s_mov_b32 m0, s4
	ds_read_b128 v[162:165], v209 offset:49152
	ds_read_b128 v[166:169], v209 offset:50176
	ds_read_b128 v[170:173], v209 offset:51200
	ds_read_b128 v[174:177], v209 offset:52224
	ds_read_b128 v[210:213], v209 offset:53248
	ds_read_b128 v[232:235], v209 offset:54272
	ds_read_b128 v[242:245], v209 offset:55296
	ds_read_b128 v[246:249], v209 offset:56320
	global_load_lds_dwordx4 v[190:191], off
	s_add_i32 m0, s4, 0x2000
	s_add_u32 s0, s0, 0x80080
	v_lshl_add_u64 v[190:191], v[204:205], 0, s[20:21]
	s_addc_u32 s1, s1, 0
	s_add_i32 s4, s31, s28
	global_load_lds_dwordx4 v[190:191], off
	v_lshl_add_u64 v[190:191], s[0:1], 0, v[96:97]
	s_mov_b32 m0, s4
	s_nop 0
	global_load_lds_dwordx4 v[190:191], off
	v_lshl_add_u64 v[190:191], s[0:1], 0, v[178:179]
	s_add_i32 m0, s4, 0x2000
	s_nop 0
	global_load_lds_dwordx4 v[190:191], off
	v_lshl_add_u64 v[190:191], v[214:215], 0, s[20:21]
	s_mov_b32 m0, s74
	s_nop 0
	global_load_lds_dwordx4 v[190:191], off
	v_lshl_add_u64 v[190:191], v[228:229], 0, s[20:21]
	s_mov_b32 m0, s75
	s_nop 0
	global_load_lds_dwordx4 v[190:191], off
	s_waitcnt vmcnt(8)
	s_waitcnt lgkmcnt(0)
	s_barrier
	v_mfma_f32_16x16x32_bf16 v[60:63], v[130:133], v[162:165], v[60:63]
	v_mfma_f32_16x16x32_bf16 v[56:59], v[138:141], v[162:165], v[56:59]
	v_mfma_f32_16x16x32_bf16 v[44:47], v[130:133], v[170:173], v[44:47]
	v_mfma_f32_16x16x32_bf16 v[40:43], v[138:141], v[170:173], v[40:43]
	v_mfma_f32_16x16x32_bf16 v[28:31], v[130:133], v[210:213], v[28:31]
	v_mfma_f32_16x16x32_bf16 v[24:27], v[138:141], v[210:213], v[24:27]
	v_mfma_f32_16x16x32_bf16 v[12:15], v[130:133], v[242:245], v[12:15]
	v_mfma_f32_16x16x32_bf16 v[8:11], v[138:141], v[242:245], v[8:11]
	v_mfma_f32_16x16x32_bf16 v[60:63], v[134:137], v[166:169], v[60:63]
	v_mfma_f32_16x16x32_bf16 v[56:59], v[142:145], v[166:169], v[56:59]
	v_mfma_f32_16x16x32_bf16 v[44:47], v[134:137], v[174:177], v[44:47]
	v_mfma_f32_16x16x32_bf16 v[40:43], v[142:145], v[174:177], v[40:43]
	v_mfma_f32_16x16x32_bf16 v[28:31], v[134:137], v[232:235], v[28:31]
	v_mfma_f32_16x16x32_bf16 v[24:27], v[142:145], v[232:235], v[24:27]
	v_mfma_f32_16x16x32_bf16 v[12:15], v[134:137], v[246:249], v[12:15]
	v_mfma_f32_16x16x32_bf16 v[8:11], v[142:145], v[246:249], v[8:11]
	v_mfma_f32_16x16x32_bf16 v[52:55], v[146:149], v[162:165], v[52:55]
	v_mfma_f32_16x16x32_bf16 v[48:51], v[154:157], v[162:165], v[48:51]
	v_mfma_f32_16x16x32_bf16 v[36:39], v[146:149], v[170:173], v[36:39]
	v_mfma_f32_16x16x32_bf16 v[32:35], v[154:157], v[170:173], v[32:35]
	v_mfma_f32_16x16x32_bf16 v[20:23], v[146:149], v[210:213], v[20:23]
	v_mfma_f32_16x16x32_bf16 v[16:19], v[154:157], v[210:213], v[16:19]
	v_mfma_f32_16x16x32_bf16 v[4:7], v[146:149], v[242:245], v[4:7]
	v_mfma_f32_16x16x32_bf16 v[0:3], v[154:157], v[242:245], v[0:3]
	v_mfma_f32_16x16x32_bf16 v[52:55], v[150:153], v[166:169], v[52:55]
	v_mfma_f32_16x16x32_bf16 v[48:51], v[158:161], v[166:169], v[48:51]
	v_mfma_f32_16x16x32_bf16 v[36:39], v[150:153], v[174:177], v[36:39]
	v_mfma_f32_16x16x32_bf16 v[32:35], v[158:161], v[174:177], v[32:35]
	s_barrier
	v_mfma_f32_16x16x32_bf16 v[20:23], v[150:153], v[232:235], v[20:23]
	v_mfma_f32_16x16x32_bf16 v[16:19], v[158:161], v[232:235], v[16:19]
	v_mfma_f32_16x16x32_bf16 v[4:7], v[150:153], v[246:249], v[4:7]
	v_mfma_f32_16x16x32_bf16 v[0:3], v[158:161], v[246:249], v[0:3]
	s_add_i32 s19, s19, 2
	s_add_u32 s15, s15, 0x100
	s_addc_u32 s17, s17, 0
	s_add_u32 s40, s40, 0x100
	s_addc_u32 s41, s41, 0
	s_cmp_gt_u32 s19, 29
	s_cbranch_scc0 .LBB0_417
	s_and_b64 vcc, exec, s[34:35]
	s_cbranch_vccz .LBB0_420
	s_barrier

; #define PG8_STAGE(bufoff, gbase, voff) do { _Pragma("unroll") for (int _i = 0; _i < 2; ++_i) \
;         __builtin_amdgcn_global_load_lds((const unsigned*)((const char*)(gbase) + (voff)[_i]), (PG8_LAS unsigned*)(lds + (bufoff) + ldsw + _i * 8192), 16, 0, 0); } while (0)
; #define PG8_LDA(dst, b, h) do { _Pragma("unroll") for (int m = 0; m < 4; ++m) _Pragma("unroll") for (int k = 0; k < 2; ++k) dst[m][k] = *(const PG8_LAS bf16x8*)(lds + PG8_SA(b, h) + aoff + m * 2048 + k * 1024); } while (0)
; #define PG8_LDB(dst, b, h) do { _Pragma("unroll") for (int n = 0; n < 2; ++n) _Pragma("unroll") for (int k = 0; k < 2; ++k) dst[n][k] = *(const PG8_LAS bf16x8*)(lds + PG8_SB(b, h) + boff + n * 2048 + k * 1024); } while (0)
; #define PG8_MMA(ai, bj, At, Bt) do { __builtin_amdgcn_s_setprio(1); _Pragma("unroll") for (int m = 0; m < 4; ++m) _Pragma("unroll") for (int n = 0; n < 2; ++n) _Pragma("unroll") for (int k = 0; k < 2; ++k) \
;         acc[ai][bj][m][n] = __builtin_amdgcn_mfma_f32_16x16x32_bf16(Bt[n][k], At[m][k], acc[ai][bj][m][n], 0, 0, 0); __builtin_amdgcn_s_setprio(0); } while (0)
; #define PG8_WAIT_V(n) asm volatile("s_waitcnt vmcnt(" #n ")" ::: "memory")
; #define PG8_WAIT_L(n) asm volatile("s_waitcnt lgkmcnt(" #n ")" ::: "memory")
; #define PG8_BAR __builtin_amdgcn_s_barrier()
; #define PG8_SCHED __builtin_amdgcn_sched_barrier(0)
; template <class Epi, class Sched, bool ALIGN_EPI = false, bool SP2 = false>
; __device__ __forceinline__ void gemm_phase(PG8_LAS unsigned char* lds, const Gemm g, const Sched& S, const Epi& E) {
;     ...
;             PG8_LDB(B0, 0, 0); PG8_LDB(B1, 0, 1); PG8_SCHED; PG8_LDA(At, 0, 0); PG8_STAGE(PG8_SA(1, 1), a1 + hstep, voffA);
;             PG8_WAIT_V(8); PG8_WAIT_L(0); PG8_BAR; PG8_MMA(0, 0, At, B0); PG8_MMA(0, 1, At, B1); PG8_BAR; PG8_SCHED;
;             PG8_LDA(At, 0, 1); PG8_STAGE(PG8_SB(0, 0), b2, voffB); PG8_STAGE(PG8_SB(0, 1), b2 + hstep, voffB); PG8_STAGE(PG8_SA(0, 0), a2, voffA);
;             PG8_WAIT_V(8); PG8_WAIT_L(0); PG8_BAR; PG8_MMA(1, 0, At, B0); PG8_MMA(1, 1, At, B1); PG8_BAR; PG8_SCHED;
.LBB0_447:
	s_add_i32 s28, s0, 2
	s_add_u32 s30, s66, 0x80
	s_addc_u32 s1, s67, 0
	s_add_i32 s33, 0, 0x10000
	s_cmp_eq_u32 s59, s0
	s_cselect_b32 s1, s43, s1
	s_cselect_b32 s0, s42, s30
	s_cselect_b32 s31, s65, s23
	s_cselect_b32 s30, s64, s17
	s_add_i32 s52, 0, 0x14000
	v_add_u32_e32 v126, s33, v232
	v_add_u32_e32 v158, s52, v232
	ds_read_b128 v[98:101], v126
	ds_read_b128 v[106:109], v126 offset:1024
	ds_read_b128 v[118:121], v126 offset:2048
	ds_read_b128 v[126:129], v126 offset:3072
	ds_read_b128 v[138:141], v158
	ds_read_b128 v[142:145], v158 offset:1024
	ds_read_b128 v[150:153], v158 offset:2048
	ds_read_b128 v[158:161], v158 offset:3072
	v_lshl_add_u64 v[212:213], s[66:67], 0, v[210:211]
	s_add_i32 m0, s4, 0xc000
	ds_read_b128 v[162:165], v234
	ds_read_b128 v[166:169], v234 offset:1024
	ds_read_b128 v[170:173], v234 offset:2048
	ds_read_b128 v[174:177], v234 offset:3072
	ds_read_b128 v[178:181], v234 offset:4096
	ds_read_b128 v[182:185], v234 offset:5120
	ds_read_b128 v[186:189], v234 offset:6144
	ds_read_b128 v[190:193], v234 offset:7168
	global_load_lds_dwordx4 v[212:213], off
	v_lshl_add_u64 v[212:213], s[66:67], 0, v[208:209]
	s_add_i32 m0, s4, 0xe000
	s_nop 0
	global_load_lds_dwordx4 v[212:213], off
	s_waitcnt vmcnt(8)
	s_waitcnt lgkmcnt(0)
	s_barrier
	v_mfma_f32_16x16x32_bf16 v[154:157], v[98:101], v[162:165], v[154:157]
	v_mfma_f32_16x16x32_bf16 v[146:149], v[118:121], v[162:165], v[146:149]
	v_mfma_f32_16x16x32_bf16 v[122:125], v[98:101], v[170:173], v[122:125]
	v_mfma_f32_16x16x32_bf16 v[114:117], v[118:121], v[170:173], v[114:117]
	v_mfma_f32_16x16x32_bf16 v[92:95], v[98:101], v[178:181], v[92:95]
	v_mfma_f32_16x16x32_bf16 v[88:91], v[118:121], v[178:181], v[88:91]
	v_mfma_f32_16x16x32_bf16 v[76:79], v[98:101], v[186:189], v[76:79]
	v_mfma_f32_16x16x32_bf16 v[72:75], v[118:121], v[186:189], v[72:75]
	v_mfma_f32_16x16x32_bf16 v[154:157], v[106:109], v[166:169], v[154:157]
	v_mfma_f32_16x16x32_bf16 v[146:149], v[126:129], v[166:169], v[146:149]
	v_mfma_f32_16x16x32_bf16 v[122:125], v[106:109], v[174:177], v[122:125]
	v_mfma_f32_16x16x32_bf16 v[114:117], v[126:129], v[174:177], v[114:117]
	v_mfma_f32_16x16x32_bf16 v[92:95], v[106:109], v[182:185], v[92:95]
	v_mfma_f32_16x16x32_bf16 v[88:91], v[126:129], v[182:185], v[88:91]
	v_mfma_f32_16x16x32_bf16 v[76:79], v[106:109], v[190:193], v[76:79]
	v_mfma_f32_16x16x32_bf16 v[72:75], v[126:129], v[190:193], v[72:75]
	v_mfma_f32_16x16x32_bf16 v[134:137], v[138:141], v[162:165], v[134:137]
	v_mfma_f32_16x16x32_bf16 v[130:133], v[150:153], v[162:165], v[130:133]
	v_mfma_f32_16x16x32_bf16 v[110:113], v[138:141], v[170:173], v[110:113]
	v_mfma_f32_16x16x32_bf16 v[102:105], v[150:153], v[170:173], v[102:105]
	v_mfma_f32_16x16x32_bf16 v[84:87], v[138:141], v[178:181], v[84:87]
	v_mfma_f32_16x16x32_bf16 v[80:83], v[150:153], v[178:181], v[80:83]
	v_mfma_f32_16x16x32_bf16 v[68:71], v[138:141], v[186:189], v[68:71]
	v_mfma_f32_16x16x32_bf16 v[64:67], v[150:153], v[186:189], v[64:67]
	v_mfma_f32_16x16x32_bf16 v[134:137], v[142:145], v[166:169], v[134:137]
	v_mfma_f32_16x16x32_bf16 v[130:133], v[158:161], v[166:169], v[130:133]
	v_mfma_f32_16x16x32_bf16 v[110:113], v[142:145], v[174:177], v[110:113]
	v_mfma_f32_16x16x32_bf16 v[102:105], v[158:161], v[174:177], v[102:105]
	s_barrier
	v_mfma_f32_16x16x32_bf16 v[84:87], v[142:145], v[182:185], v[84:87]
	v_mfma_f32_16x16x32_bf16 v[80:83], v[158:161], v[182:185], v[80:83]
	v_mfma_f32_16x16x32_bf16 v[68:71], v[142:145], v[190:193], v[68:71]
	v_mfma_f32_16x16x32_bf16 v[64:67], v[158:161], v[190:193], v[64:67]
	s_add_i32 s33, s33, s2
	v_lshl_add_u64 v[212:213], s[30:31], 0, v[96:97]
	s_mov_b32 m0, s33
	ds_read_b128 v[162:165], v234 offset:16384
	ds_read_b128 v[166:169], v234 offset:17408
	ds_read_b128 v[170:173], v234 offset:18432
	ds_read_b128 v[174:177], v234 offset:19456
	ds_read_b128 v[178:181], v234 offset:20480
	ds_read_b128 v[182:185], v234 offset:21504
	ds_read_b128 v[186:189], v234 offset:22528
	ds_read_b128 v[190:193], v234 offset:23552
	global_load_lds_dwordx4 v[212:213], off
	s_add_i32 m0, s33, 0x2000
	v_lshl_add_u64 v[214:215], s[30:31], 0, v[202:203]
	s_add_u32 s30, s30, s22
	s_addc_u32 s31, s31, 0
	s_add_i32 s33, s52, s2
	global_load_lds_dwordx4 v[214:215], off
	v_lshl_add_u64 v[228:229], s[30:31], 0, v[96:97]
	s_mov_b32 m0, s33
	v_lshl_add_u64 v[236:237], s[30:31], 0, v[202:203]
	global_load_lds_dwordx4 v[228:229], off
	s_add_i32 m0, s33, 0x2000
	v_lshl_add_u64 v[242:243], s[0:1], 0, v[206:207]
	global_load_lds_dwordx4 v[236:237], off
	s_mov_b32 m0, s4
	v_lshl_add_u64 v[244:245], s[0:1], 0, v[204:205]
	global_load_lds_dwordx4 v[242:243], off
	s_mov_b32 m0, s5
	s_nop 0
	global_load_lds_dwordx4 v[244:245], off
	s_waitcnt vmcnt(8)
	s_waitcnt lgkmcnt(0)
	s_barrier
; #define PG8_STAGE(bufoff, gbase, voff) do { _Pragma("unroll") for (int _i = 0; _i < 2; ++_i) \
;         __builtin_amdgcn_global_load_lds((const unsigned*)((const char*)(gbase) + (voff)[_i]), (PG8_LAS unsigned*)(lds + (bufoff) + ldsw + _i * 8192), 16, 0, 0); } while (0)
; #define PG8_LDA(dst, b, h) do { _Pragma("unroll") for (int m = 0; m < 4; ++m) _Pragma("unroll") for (int k = 0; k < 2; ++k) dst[m][k] = *(const PG8_LAS bf16x8*)(lds + PG8_SA(b, h) + aoff + m * 2048 + k * 1024); } while (0)
; #define PG8_LDB(dst, b, h) do { _Pragma("unroll") for (int n = 0; n < 2; ++n) _Pragma("unroll") for (int k = 0; k < 2; ++k) dst[n][k] = *(const PG8_LAS bf16x8*)(lds + PG8_SB(b, h) + boff + n * 2048 + k * 1024); } while (0)
; #define PG8_MMA(ai, bj, At, Bt) do { __builtin_amdgcn_s_setprio(1); _Pragma("unroll") for (int m = 0; m < 4; ++m) _Pragma("unroll") for (int n = 0; n < 2; ++n) _Pragma("unroll") for (int k = 0; k < 2; ++k) \
;         acc[ai][bj][m][n] = __builtin_amdgcn_mfma_f32_16x16x32_bf16(Bt[n][k], At[m][k], acc[ai][bj][m][n], 0, 0, 0); __builtin_amdgcn_s_setprio(0); } while (0)
; #define PG8_WAIT_V(n) asm volatile("s_waitcnt vmcnt(" #n ")" ::: "memory")
; #define PG8_WAIT_L(n) asm volatile("s_waitcnt lgkmcnt(" #n ")" ::: "memory")
; #define PG8_BAR __builtin_amdgcn_s_barrier()
; #define PG8_SCHED __builtin_amdgcn_sched_barrier(0)
; template <class Epi, class Sched, bool ALIGN_EPI = false, bool SP2 = false>
; __device__ __forceinline__ void gemm_phase(PG8_LAS unsigned char* lds, const Gemm g, const Sched& S, const Epi& E) {
;     ...
;             PG8_WAIT_V(8); PG8_WAIT_L(0); PG8_BAR; PG8_MMA(1, 0, At, B0); PG8_MMA(1, 1, At, B1); PG8_BAR; PG8_SCHED;
;             PG8_LDB(B0, 1, 0); PG8_LDB(B1, 1, 1); PG8_SCHED; PG8_LDA(At, 1, 0); PG8_STAGE(PG8_SA(0, 1), a2 + hstep, voffA);
;             PG8_WAIT_V(8); PG8_WAIT_L(0); PG8_BAR; PG8_MMA(0, 0, At, B0); PG8_MMA(0, 1, At, B1); PG8_BAR; PG8_SCHED;
	v_mfma_f32_16x16x32_bf16 v[60:63], v[98:101], v[162:165], v[60:63]
	v_mfma_f32_16x16x32_bf16 v[56:59], v[118:121], v[162:165], v[56:59]
	v_mfma_f32_16x16x32_bf16 v[44:47], v[98:101], v[170:173], v[44:47]
	v_mfma_f32_16x16x32_bf16 v[40:43], v[118:121], v[170:173], v[40:43]
	v_mfma_f32_16x16x32_bf16 v[28:31], v[98:101], v[178:181], v[28:31]
	v_mfma_f32_16x16x32_bf16 v[24:27], v[118:121], v[178:181], v[24:27]
	v_mfma_f32_16x16x32_bf16 v[12:15], v[98:101], v[186:189], v[12:15]
	v_mfma_f32_16x16x32_bf16 v[8:11], v[118:121], v[186:189], v[8:11]
	v_mfma_f32_16x16x32_bf16 v[60:63], v[106:109], v[166:169], v[60:63]
	v_mfma_f32_16x16x32_bf16 v[56:59], v[126:129], v[166:169], v[56:59]
	v_mfma_f32_16x16x32_bf16 v[44:47], v[106:109], v[174:177], v[44:47]
	v_mfma_f32_16x16x32_bf16 v[40:43], v[126:129], v[174:177], v[40:43]
	v_mfma_f32_16x16x32_bf16 v[28:31], v[106:109], v[182:185], v[28:31]
	v_mfma_f32_16x16x32_bf16 v[24:27], v[126:129], v[182:185], v[24:27]
	v_mfma_f32_16x16x32_bf16 v[12:15], v[106:109], v[190:193], v[12:15]
	v_mfma_f32_16x16x32_bf16 v[8:11], v[126:129], v[190:193], v[8:11]
	v_mfma_f32_16x16x32_bf16 v[52:55], v[138:141], v[162:165], v[52:55]
	v_mfma_f32_16x16x32_bf16 v[48:51], v[150:153], v[162:165], v[48:51]
	v_mfma_f32_16x16x32_bf16 v[36:39], v[138:141], v[170:173], v[36:39]
	v_mfma_f32_16x16x32_bf16 v[32:35], v[150:153], v[170:173], v[32:35]
	v_mfma_f32_16x16x32_bf16 v[20:23], v[138:141], v[178:181], v[20:23]
	v_mfma_f32_16x16x32_bf16 v[16:19], v[150:153], v[178:181], v[16:19]
	v_mfma_f32_16x16x32_bf16 v[4:7], v[138:141], v[186:189], v[4:7]
	v_mfma_f32_16x16x32_bf16 v[0:3], v[150:153], v[186:189], v[0:3]
	v_mfma_f32_16x16x32_bf16 v[52:55], v[142:145], v[166:169], v[52:55]
	v_mfma_f32_16x16x32_bf16 v[48:51], v[158:161], v[166:169], v[48:51]
	v_mfma_f32_16x16x32_bf16 v[36:39], v[142:145], v[174:177], v[36:39]
	v_mfma_f32_16x16x32_bf16 v[32:35], v[158:161], v[174:177], v[32:35]
	s_barrier
	v_mfma_f32_16x16x32_bf16 v[20:23], v[142:145], v[182:185], v[20:23]
	v_mfma_f32_16x16x32_bf16 v[16:19], v[158:161], v[182:185], v[16:19]
	v_mfma_f32_16x16x32_bf16 v[4:7], v[142:145], v[190:193], v[4:7]
	v_mfma_f32_16x16x32_bf16 v[0:3], v[158:161], v[190:193], v[0:3]
	s_add_i32 s30, 0, 0x18000
	s_add_i32 s31, 0, 0x1c000
	v_add_u32_e32 v126, s30, v232
	v_add_u32_e32 v158, s31, v232
	ds_read_b128 v[98:101], v126
	ds_read_b128 v[106:109], v126 offset:1024
	ds_read_b128 v[118:121], v126 offset:2048
	ds_read_b128 v[126:129], v126 offset:3072
	ds_read_b128 v[138:141], v158
	ds_read_b128 v[142:145], v158 offset:1024
	ds_read_b128 v[150:153], v158 offset:2048
	ds_read_b128 v[158:161], v158 offset:3072
	s_add_u32 s0, s0, s22
	s_addc_u32 s1, s1, 0
	s_mov_b32 m0, s14
	v_lshl_add_u64 v[246:247], s[0:1], 0, v[206:207]
	ds_read_b128 v[162:165], v234 offset:32768
	ds_read_b128 v[166:169], v234 offset:33792
	ds_read_b128 v[170:173], v234 offset:34816
	ds_read_b128 v[174:177], v234 offset:35840
	ds_read_b128 v[178:181], v234 offset:36864
	ds_read_b128 v[182:185], v234 offset:37888
	ds_read_b128 v[186:189], v234 offset:38912
	ds_read_b128 v[190:193], v234 offset:39936
	global_load_lds_dwordx4 v[246:247], off
	v_lshl_add_u64 v[246:247], s[0:1], 0, v[204:205]
	s_mov_b32 m0, s15
	s_nop 0
	global_load_lds_dwordx4 v[246:247], off
	s_waitcnt vmcnt(8)
	s_waitcnt lgkmcnt(0)
	s_barrier
	v_mfma_f32_16x16x32_bf16 v[154:157], v[98:101], v[162:165], v[154:157]
	v_mfma_f32_16x16x32_bf16 v[146:149], v[118:121], v[162:165], v[146:149]
	v_mfma_f32_16x16x32_bf16 v[122:125], v[98:101], v[170:173], v[122:125]
	v_mfma_f32_16x16x32_bf16 v[114:117], v[118:121], v[170:173], v[114:117]
	v_mfma_f32_16x16x32_bf16 v[92:95], v[98:101], v[178:181], v[92:95]
	v_mfma_f32_16x16x32_bf16 v[88:91], v[118:121], v[178:181], v[88:91]
	v_mfma_f32_16x16x32_bf16 v[76:79], v[98:101], v[186:189], v[76:79]
	v_mfma_f32_16x16x32_bf16 v[72:75], v[118:121], v[186:189], v[72:75]
	v_mfma_f32_16x16x32_bf16 v[154:157], v[106:109], v[166:169], v[154:157]
	v_mfma_f32_16x16x32_bf16 v[146:149], v[126:129], v[166:169], v[146:149]
	v_mfma_f32_16x16x32_bf16 v[122:125], v[106:109], v[174:177], v[122:125]
	v_mfma_f32_16x16x32_bf16 v[114:117], v[126:129], v[174:177], v[114:117]
	v_mfma_f32_16x16x32_bf16 v[92:95], v[106:109], v[182:185], v[92:95]
	v_mfma_f32_16x16x32_bf16 v[88:91], v[126:129], v[182:185], v[88:91]
	v_mfma_f32_16x16x32_bf16 v[76:79], v[106:109], v[190:193], v[76:79]
	v_mfma_f32_16x16x32_bf16 v[72:75], v[126:129], v[190:193], v[72:75]
	v_mfma_f32_16x16x32_bf16 v[134:137], v[138:141], v[162:165], v[134:137]
	v_mfma_f32_16x16x32_bf16 v[130:133], v[150:153], v[162:165], v[130:133]
	v_mfma_f32_16x16x32_bf16 v[110:113], v[138:141], v[170:173], v[110:113]
	v_mfma_f32_16x16x32_bf16 v[102:105], v[150:153], v[170:173], v[102:105]
	v_mfma_f32_16x16x32_bf16 v[84:87], v[138:141], v[178:181], v[84:87]
	v_mfma_f32_16x16x32_bf16 v[80:83], v[150:153], v[178:181], v[80:83]
	v_mfma_f32_16x16x32_bf16 v[68:71], v[138:141], v[186:189], v[68:71]
	v_mfma_f32_16x16x32_bf16 v[64:67], v[150:153], v[186:189], v[64:67]
	v_mfma_f32_16x16x32_bf16 v[134:137], v[142:145], v[166:169], v[134:137]
	v_mfma_f32_16x16x32_bf16 v[130:133], v[158:161], v[166:169], v[130:133]
	v_mfma_f32_16x16x32_bf16 v[110:113], v[142:145], v[174:177], v[110:113]
	v_mfma_f32_16x16x32_bf16 v[102:105], v[158:161], v[174:177], v[102:105]
	s_barrier
; #define PG8_STAGE(bufoff, gbase, voff) do { _Pragma("unroll") for (int _i = 0; _i < 2; ++_i) \
;         __builtin_amdgcn_global_load_lds((const unsigned*)((const char*)(gbase) + (voff)[_i]), (PG8_LAS unsigned*)(lds + (bufoff) + ldsw + _i * 8192), 16, 0, 0); } while (0)
; #define PG8_LDA(dst, b, h) do { _Pragma("unroll") for (int m = 0; m < 4; ++m) _Pragma("unroll") for (int k = 0; k < 2; ++k) dst[m][k] = *(const PG8_LAS bf16x8*)(lds + PG8_SA(b, h) + aoff + m * 2048 + k * 1024); } while (0)
; #define PG8_MMA(ai, bj, At, Bt) do { __builtin_amdgcn_s_setprio(1); _Pragma("unroll") for (int m = 0; m < 4; ++m) _Pragma("unroll") for (int n = 0; n < 2; ++n) _Pragma("unroll") for (int k = 0; k < 2; ++k) \
;         acc[ai][bj][m][n] = __builtin_amdgcn_mfma_f32_16x16x32_bf16(Bt[n][k], At[m][k], acc[ai][bj][m][n], 0, 0, 0); __builtin_amdgcn_s_setprio(0); } while (0)
; #define PG8_WAIT_V(n) asm volatile("s_waitcnt vmcnt(" #n ")" ::: "memory")
; #define PG8_WAIT_L(n) asm volatile("s_waitcnt lgkmcnt(" #n ")" ::: "memory")
; #define PG8_BAR __builtin_amdgcn_s_barrier()
; #define PG8_SCHED __builtin_amdgcn_sched_barrier(0)
; template <class Epi, class Sched, bool ALIGN_EPI = false, bool SP2 = false>
; __device__ __forceinline__ void gemm_phase(PG8_LAS unsigned char* lds, const Gemm g, const Sched& S, const Epi& E) {
;     ...
;             PG8_LDA(At, 1, 1); PG8_STAGE(PG8_SB(1, 0), b3, voffB); PG8_STAGE(PG8_SB(1, 1), b3 + hstep, voffB); PG8_STAGE(PG8_SA(1, 0), a3, voffA);
;             PG8_WAIT_V(8); PG8_WAIT_L(0); PG8_BAR; PG8_MMA(1, 0, At, B0); PG8_MMA(1, 1, At, B1); PG8_BAR; PG8_SCHED;
	v_mfma_f32_16x16x32_bf16 v[84:87], v[142:145], v[182:185], v[84:87]
	v_mfma_f32_16x16x32_bf16 v[80:83], v[158:161], v[182:185], v[80:83]
	v_mfma_f32_16x16x32_bf16 v[68:71], v[142:145], v[190:193], v[68:71]
	v_mfma_f32_16x16x32_bf16 v[64:67], v[158:161], v[190:193], v[64:67]
	s_add_i32 s0, s30, s2
	v_lshl_add_u64 v[212:213], v[212:213], 0, s[20:21]
	s_mov_b32 m0, s0
	ds_read_b128 v[162:165], v234 offset:49152
	ds_read_b128 v[166:169], v234 offset:50176
	ds_read_b128 v[170:173], v234 offset:51200
	ds_read_b128 v[174:177], v234 offset:52224
	ds_read_b128 v[178:181], v234 offset:53248
	ds_read_b128 v[182:185], v234 offset:54272
	ds_read_b128 v[186:189], v234 offset:55296
	ds_read_b128 v[190:193], v234 offset:56320
	global_load_lds_dwordx4 v[212:213], off
	v_lshl_add_u64 v[212:213], v[214:215], 0, s[20:21]
	s_add_i32 m0, s0, 0x2000
	s_add_i32 s0, s31, s2
	global_load_lds_dwordx4 v[212:213], off
	v_lshl_add_u64 v[212:213], v[228:229], 0, s[20:21]
	s_mov_b32 m0, s0
	s_nop 0
	global_load_lds_dwordx4 v[212:213], off
	v_lshl_add_u64 v[212:213], v[236:237], 0, s[20:21]
	s_add_i32 m0, s0, 0x2000
	s_nop 0
	global_load_lds_dwordx4 v[212:213], off
	v_lshl_add_u64 v[212:213], v[242:243], 0, s[20:21]
	s_mov_b32 m0, s19
	s_nop 0
	global_load_lds_dwordx4 v[212:213], off
	v_lshl_add_u64 v[212:213], v[244:245], 0, s[20:21]
	s_mov_b32 m0, s46
	s_nop 0
	global_load_lds_dwordx4 v[212:213], off
	s_waitcnt vmcnt(8)
	s_waitcnt lgkmcnt(0)
	s_barrier
	v_mfma_f32_16x16x32_bf16 v[60:63], v[98:101], v[162:165], v[60:63]
	v_mfma_f32_16x16x32_bf16 v[56:59], v[118:121], v[162:165], v[56:59]
	v_mfma_f32_16x16x32_bf16 v[44:47], v[98:101], v[170:173], v[44:47]
	v_mfma_f32_16x16x32_bf16 v[40:43], v[118:121], v[170:173], v[40:43]
	v_mfma_f32_16x16x32_bf16 v[28:31], v[98:101], v[178:181], v[28:31]
	v_mfma_f32_16x16x32_bf16 v[24:27], v[118:121], v[178:181], v[24:27]
	v_mfma_f32_16x16x32_bf16 v[12:15], v[98:101], v[186:189], v[12:15]
	v_mfma_f32_16x16x32_bf16 v[8:11], v[118:121], v[186:189], v[8:11]
	v_mfma_f32_16x16x32_bf16 v[60:63], v[106:109], v[166:169], v[60:63]
	v_mfma_f32_16x16x32_bf16 v[56:59], v[126:129], v[166:169], v[56:59]
	v_mfma_f32_16x16x32_bf16 v[44:47], v[106:109], v[174:177], v[44:47]
	v_mfma_f32_16x16x32_bf16 v[40:43], v[126:129], v[174:177], v[40:43]
	v_mfma_f32_16x16x32_bf16 v[28:31], v[106:109], v[182:185], v[28:31]
	v_mfma_f32_16x16x32_bf16 v[24:27], v[126:129], v[182:185], v[24:27]
	v_mfma_f32_16x16x32_bf16 v[12:15], v[106:109], v[190:193], v[12:15]
	v_mfma_f32_16x16x32_bf16 v[8:11], v[126:129], v[190:193], v[8:11]
	v_mfma_f32_16x16x32_bf16 v[52:55], v[138:141], v[162:165], v[52:55]
	v_mfma_f32_16x16x32_bf16 v[48:51], v[150:153], v[162:165], v[48:51]
	v_mfma_f32_16x16x32_bf16 v[36:39], v[138:141], v[170:173], v[36:39]
	v_mfma_f32_16x16x32_bf16 v[32:35], v[150:153], v[170:173], v[32:35]
	v_mfma_f32_16x16x32_bf16 v[20:23], v[138:141], v[178:181], v[20:23]
	v_mfma_f32_16x16x32_bf16 v[16:19], v[150:153], v[178:181], v[16:19]
	v_mfma_f32_16x16x32_bf16 v[4:7], v[138:141], v[186:189], v[4:7]
	v_mfma_f32_16x16x32_bf16 v[0:3], v[150:153], v[186:189], v[0:3]
	v_mfma_f32_16x16x32_bf16 v[52:55], v[142:145], v[166:169], v[52:55]
	v_mfma_f32_16x16x32_bf16 v[48:51], v[158:161], v[166:169], v[48:51]
	v_mfma_f32_16x16x32_bf16 v[36:39], v[142:145], v[174:177], v[36:39]
	v_mfma_f32_16x16x32_bf16 v[32:35], v[158:161], v[174:177], v[32:35]
	s_barrier
	v_mfma_f32_16x16x32_bf16 v[20:23], v[142:145], v[182:185], v[20:23]
	v_mfma_f32_16x16x32_bf16 v[16:19], v[158:161], v[182:185], v[16:19]
	v_mfma_f32_16x16x32_bf16 v[4:7], v[142:145], v[190:193], v[4:7]
	v_mfma_f32_16x16x32_bf16 v[0:3], v[158:161], v[190:193], v[0:3]
	s_add_u32 s17, s17, 0x100
	s_addc_u32 s23, s23, 0
	s_add_u32 s66, s66, 0x100
	s_addc_u32 s67, s67, 0
	s_cmp_ge_u32 s28, s49
	s_mov_b32 s0, s28
	s_cbranch_scc0 .LBB0_447
	s_and_b64 vcc, exec, s[62:63]
	s_cbranch_vccz .LBB0_450
	s_barrier

; #define PG8_STAGE(bufoff, gbase, voff) do { _Pragma("unroll") for (int _i = 0; _i < 2; ++_i) \
;         __builtin_amdgcn_global_load_lds((const unsigned*)((const char*)(gbase) + (voff)[_i]), (PG8_LAS unsigned*)(lds + (bufoff) + ldsw + _i * 8192), 16, 0, 0); } while (0)
; #define PG8_LDA(dst, b, h) do { _Pragma("unroll") for (int m = 0; m < 4; ++m) _Pragma("unroll") for (int k = 0; k < 2; ++k) dst[m][k] = *(const PG8_LAS bf16x8*)(lds + PG8_SA(b, h) + aoff + m * 2048 + k * 1024); } while (0)
; #define PG8_LDB(dst, b, h) do { _Pragma("unroll") for (int n = 0; n < 2; ++n) _Pragma("unroll") for (int k = 0; k < 2; ++k) dst[n][k] = *(const PG8_LAS bf16x8*)(lds + PG8_SB(b, h) + boff + n * 2048 + k * 1024); } while (0)
; #define PG8_MMA(ai, bj, At, Bt) do { __builtin_amdgcn_s_setprio(1); _Pragma("unroll") for (int m = 0; m < 4; ++m) _Pragma("unroll") for (int n = 0; n < 2; ++n) _Pragma("unroll") for (int k = 0; k < 2; ++k) \
;         acc[ai][bj][m][n] = __builtin_amdgcn_mfma_f32_16x16x32_bf16(Bt[n][k], At[m][k], acc[ai][bj][m][n], 0, 0, 0); __builtin_amdgcn_s_setprio(0); } while (0)
; #define PG8_WAIT_V(n) asm volatile("s_waitcnt vmcnt(" #n ")" ::: "memory")
; #define PG8_WAIT_L(n) asm volatile("s_waitcnt lgkmcnt(" #n ")" ::: "memory")
; #define PG8_BAR __builtin_amdgcn_s_barrier()
; #define PG8_SCHED __builtin_amdgcn_sched_barrier(0)
; template <class Epi, class Sched, bool ALIGN_EPI = false, bool SP2 = false>
; __device__ __forceinline__ void gemm_phase(PG8_LAS unsigned char* lds, const Gemm g, const Sched& S, const Epi& E) {
;     ...
;             PG8_LDB(B0, 0, 0); PG8_LDB(B1, 0, 1); PG8_SCHED; PG8_LDA(At, 0, 0); PG8_STAGE(PG8_SA(1, 1), a1 + hstep, voffA);
;             PG8_WAIT_V(8); PG8_WAIT_L(0); PG8_BAR; PG8_MMA(0, 0, At, B0); PG8_MMA(0, 1, At, B1); PG8_BAR; PG8_SCHED;
;             PG8_LDA(At, 0, 1); PG8_STAGE(PG8_SB(0, 0), b2, voffB); PG8_STAGE(PG8_SB(0, 1), b2 + hstep, voffB); PG8_STAGE(PG8_SA(0, 0), a2, voffA);
;             PG8_WAIT_V(8); PG8_WAIT_L(0); PG8_BAR; PG8_MMA(1, 0, At, B0); PG8_MMA(1, 1, At, B1); PG8_BAR; PG8_SCHED;
.LBB0_510:
	s_add_i32 s95, s0, 2
	s_add_u32 s96, s40, 0x80
	s_addc_u32 s1, s41, 0
	s_add_i32 vcc_lo, 0, 0x10000
	s_cmp_eq_u32 s7, s0
	s_cselect_b32 s1, s89, s1
	s_cselect_b32 s0, s88, s96
	s_cselect_b32 s97, s87, s94
	s_cselect_b32 s96, s86, s45
	s_add_i32 vcc_hi, 0, 0x14000
	v_add_u32_e32 v142, vcc_lo, v193
	v_add_u32_e32 v158, vcc_hi, v193
	ds_read_b128 v[130:133], v142
	ds_read_b128 v[134:137], v142 offset:1024
	ds_read_b128 v[138:141], v142 offset:2048
	ds_read_b128 v[142:145], v142 offset:3072
	ds_read_b128 v[146:149], v158
	ds_read_b128 v[150:153], v158 offset:1024
	ds_read_b128 v[154:157], v158 offset:2048
	ds_read_b128 v[158:161], v158 offset:3072
	v_lshl_add_u64 v[202:203], s[40:41], 0, v[188:189]
	s_add_i32 m0, s90, 0xc000
	ds_read_b128 v[162:165], v207
	ds_read_b128 v[166:169], v207 offset:1024
	ds_read_b128 v[170:173], v207 offset:2048
	ds_read_b128 v[174:177], v207 offset:3072
	ds_read_b128 v[208:211], v207 offset:4096
	ds_read_b128 v[212:215], v207 offset:5120
	ds_read_b128 v[232:235], v207 offset:6144
	ds_read_b128 v[242:245], v207 offset:7168
	global_load_lds_dwordx4 v[202:203], off
	v_lshl_add_u64 v[202:203], s[40:41], 0, v[186:187]
	s_add_i32 m0, s90, 0xe000
	s_nop 0
	global_load_lds_dwordx4 v[202:203], off
	s_waitcnt vmcnt(8)
	s_waitcnt lgkmcnt(0)
	s_barrier
	v_mfma_f32_16x16x32_bf16 v[126:129], v[130:133], v[162:165], v[126:129]
	v_mfma_f32_16x16x32_bf16 v[122:125], v[138:141], v[162:165], v[122:125]
	v_mfma_f32_16x16x32_bf16 v[114:117], v[130:133], v[170:173], v[114:117]
	v_mfma_f32_16x16x32_bf16 v[106:109], v[138:141], v[170:173], v[106:109]
	v_mfma_f32_16x16x32_bf16 v[98:101], v[130:133], v[208:211], v[98:101]
	v_mfma_f32_16x16x32_bf16 v[88:91], v[138:141], v[208:211], v[88:91]
	v_mfma_f32_16x16x32_bf16 v[80:83], v[130:133], v[232:235], v[80:83]
	v_mfma_f32_16x16x32_bf16 v[72:75], v[138:141], v[232:235], v[72:75]
	v_mfma_f32_16x16x32_bf16 v[126:129], v[134:137], v[166:169], v[126:129]
	v_mfma_f32_16x16x32_bf16 v[122:125], v[142:145], v[166:169], v[122:125]
	v_mfma_f32_16x16x32_bf16 v[114:117], v[134:137], v[174:177], v[114:117]
	v_mfma_f32_16x16x32_bf16 v[106:109], v[142:145], v[174:177], v[106:109]
	v_mfma_f32_16x16x32_bf16 v[98:101], v[134:137], v[212:215], v[98:101]
	v_mfma_f32_16x16x32_bf16 v[88:91], v[142:145], v[212:215], v[88:91]
	v_mfma_f32_16x16x32_bf16 v[80:83], v[134:137], v[242:245], v[80:83]
	v_mfma_f32_16x16x32_bf16 v[72:75], v[142:145], v[242:245], v[72:75]
	v_mfma_f32_16x16x32_bf16 v[118:121], v[146:149], v[162:165], v[118:121]
	v_mfma_f32_16x16x32_bf16 v[110:113], v[154:157], v[162:165], v[110:113]
	v_mfma_f32_16x16x32_bf16 v[102:105], v[146:149], v[170:173], v[102:105]
	v_mfma_f32_16x16x32_bf16 v[92:95], v[154:157], v[170:173], v[92:95]
	v_mfma_f32_16x16x32_bf16 v[84:87], v[146:149], v[208:211], v[84:87]
	v_mfma_f32_16x16x32_bf16 v[76:79], v[154:157], v[208:211], v[76:79]
	v_mfma_f32_16x16x32_bf16 v[68:71], v[146:149], v[232:235], v[68:71]
	v_mfma_f32_16x16x32_bf16 v[64:67], v[154:157], v[232:235], v[64:67]
	v_mfma_f32_16x16x32_bf16 v[118:121], v[150:153], v[166:169], v[118:121]
	v_mfma_f32_16x16x32_bf16 v[110:113], v[158:161], v[166:169], v[110:113]
	v_mfma_f32_16x16x32_bf16 v[102:105], v[150:153], v[174:177], v[102:105]
	v_mfma_f32_16x16x32_bf16 v[92:95], v[158:161], v[174:177], v[92:95]
	s_barrier
	v_mfma_f32_16x16x32_bf16 v[84:87], v[150:153], v[212:215], v[84:87]
	v_mfma_f32_16x16x32_bf16 v[76:79], v[158:161], v[212:215], v[76:79]
	v_mfma_f32_16x16x32_bf16 v[68:71], v[150:153], v[242:245], v[68:71]
	v_mfma_f32_16x16x32_bf16 v[64:67], v[158:161], v[242:245], v[64:67]
	s_add_i32 vcc_lo, vcc_lo, s4
	v_lshl_add_u64 v[202:203], s[96:97], 0, v[96:97]
	s_mov_b32 m0, vcc_lo
	ds_read_b128 v[162:165], v207 offset:16384
	ds_read_b128 v[166:169], v207 offset:17408
	ds_read_b128 v[170:173], v207 offset:18432
	ds_read_b128 v[174:177], v207 offset:19456
	ds_read_b128 v[208:211], v207 offset:20480
	ds_read_b128 v[212:215], v207 offset:21504
	ds_read_b128 v[232:235], v207 offset:22528
	ds_read_b128 v[242:245], v207 offset:23552
	global_load_lds_dwordx4 v[202:203], off
	s_add_i32 m0, vcc_lo, 0x2000
	v_lshl_add_u64 v[228:229], s[96:97], 0, v[178:179]
	s_add_u32 s96, s96, s28
	s_addc_u32 s97, s97, 0
	s_add_i32 vcc_lo, vcc_hi, s4
	global_load_lds_dwordx4 v[228:229], off
	v_lshl_add_u64 v[230:231], s[96:97], 0, v[96:97]
	s_mov_b32 m0, vcc_lo
	v_lshl_add_u64 v[246:247], s[96:97], 0, v[178:179]
	global_load_lds_dwordx4 v[230:231], off
	s_add_i32 m0, vcc_lo, 0x2000
	v_lshl_add_u64 v[248:249], s[0:1], 0, v[182:183]
	global_load_lds_dwordx4 v[246:247], off
	s_mov_b32 m0, s90
	v_lshl_add_u64 v[236:237], s[0:1], 0, v[180:181]
	global_load_lds_dwordx4 v[248:249], off
	s_mov_b32 m0, s8
	s_nop 0
	global_load_lds_dwordx4 v[236:237], off
	s_waitcnt vmcnt(8)
	s_waitcnt lgkmcnt(0)
	s_barrier
; #define PG8_STAGE(bufoff, gbase, voff) do { _Pragma("unroll") for (int _i = 0; _i < 2; ++_i) \
;         __builtin_amdgcn_global_load_lds((const unsigned*)((const char*)(gbase) + (voff)[_i]), (PG8_LAS unsigned*)(lds + (bufoff) + ldsw + _i * 8192), 16, 0, 0); } while (0)
; #define PG8_LDA(dst, b, h) do { _Pragma("unroll") for (int m = 0; m < 4; ++m) _Pragma("unroll") for (int k = 0; k < 2; ++k) dst[m][k] = *(const PG8_LAS bf16x8*)(lds + PG8_SA(b, h) + aoff + m * 2048 + k * 1024); } while (0)
; #define PG8_LDB(dst, b, h) do { _Pragma("unroll") for (int n = 0; n < 2; ++n) _Pragma("unroll") for (int k = 0; k < 2; ++k) dst[n][k] = *(const PG8_LAS bf16x8*)(lds + PG8_SB(b, h) + boff + n * 2048 + k * 1024); } while (0)
; #define PG8_MMA(ai, bj, At, Bt) do { __builtin_amdgcn_s_setprio(1); _Pragma("unroll") for (int m = 0; m < 4; ++m) _Pragma("unroll") for (int n = 0; n < 2; ++n) _Pragma("unroll") for (int k = 0; k < 2; ++k) \
;         acc[ai][bj][m][n] = __builtin_amdgcn_mfma_f32_16x16x32_bf16(Bt[n][k], At[m][k], acc[ai][bj][m][n], 0, 0, 0); __builtin_amdgcn_s_setprio(0); } while (0)
; #define PG8_WAIT_V(n) asm volatile("s_waitcnt vmcnt(" #n ")" ::: "memory")
; #define PG8_WAIT_L(n) asm volatile("s_waitcnt lgkmcnt(" #n ")" ::: "memory")
; #define PG8_BAR __builtin_amdgcn_s_barrier()
; #define PG8_SCHED __builtin_amdgcn_sched_barrier(0)
; template <class Epi, class Sched, bool ALIGN_EPI = false, bool SP2 = false>
; __device__ __forceinline__ void gemm_phase(PG8_LAS unsigned char* lds, const Gemm g, const Sched& S, const Epi& E) {
;     ...
;             PG8_WAIT_V(8); PG8_WAIT_L(0); PG8_BAR; PG8_MMA(1, 0, At, B0); PG8_MMA(1, 1, At, B1); PG8_BAR; PG8_SCHED;
;             PG8_LDB(B0, 1, 0); PG8_LDB(B1, 1, 1); PG8_SCHED; PG8_LDA(At, 1, 0); PG8_STAGE(PG8_SA(0, 1), a2 + hstep, voffA);
;             PG8_WAIT_V(8); PG8_WAIT_L(0); PG8_BAR; PG8_MMA(0, 0, At, B0); PG8_MMA(0, 1, At, B1); PG8_BAR; PG8_SCHED;
	v_mfma_f32_16x16x32_bf16 v[60:63], v[130:133], v[162:165], v[60:63]
	v_mfma_f32_16x16x32_bf16 v[56:59], v[138:141], v[162:165], v[56:59]
	v_mfma_f32_16x16x32_bf16 v[48:51], v[130:133], v[170:173], v[48:51]
	v_mfma_f32_16x16x32_bf16 v[40:43], v[138:141], v[170:173], v[40:43]
	v_mfma_f32_16x16x32_bf16 v[32:35], v[130:133], v[208:211], v[32:35]
	v_mfma_f32_16x16x32_bf16 v[24:27], v[138:141], v[208:211], v[24:27]
	v_mfma_f32_16x16x32_bf16 v[16:19], v[130:133], v[232:235], v[16:19]
	v_mfma_f32_16x16x32_bf16 v[8:11], v[138:141], v[232:235], v[8:11]
	v_mfma_f32_16x16x32_bf16 v[60:63], v[134:137], v[166:169], v[60:63]
	v_mfma_f32_16x16x32_bf16 v[56:59], v[142:145], v[166:169], v[56:59]
	v_mfma_f32_16x16x32_bf16 v[48:51], v[134:137], v[174:177], v[48:51]
	v_mfma_f32_16x16x32_bf16 v[40:43], v[142:145], v[174:177], v[40:43]
	v_mfma_f32_16x16x32_bf16 v[32:35], v[134:137], v[212:215], v[32:35]
	v_mfma_f32_16x16x32_bf16 v[24:27], v[142:145], v[212:215], v[24:27]
	v_mfma_f32_16x16x32_bf16 v[16:19], v[134:137], v[242:245], v[16:19]
	v_mfma_f32_16x16x32_bf16 v[8:11], v[142:145], v[242:245], v[8:11]
	v_mfma_f32_16x16x32_bf16 v[52:55], v[146:149], v[162:165], v[52:55]
	v_mfma_f32_16x16x32_bf16 v[44:47], v[154:157], v[162:165], v[44:47]
	v_mfma_f32_16x16x32_bf16 v[36:39], v[146:149], v[170:173], v[36:39]
	v_mfma_f32_16x16x32_bf16 v[28:31], v[154:157], v[170:173], v[28:31]
	v_mfma_f32_16x16x32_bf16 v[20:23], v[146:149], v[208:211], v[20:23]
	v_mfma_f32_16x16x32_bf16 v[12:15], v[154:157], v[208:211], v[12:15]
	v_mfma_f32_16x16x32_bf16 v[4:7], v[146:149], v[232:235], v[4:7]
	v_mfma_f32_16x16x32_bf16 v[0:3], v[154:157], v[232:235], v[0:3]
	v_mfma_f32_16x16x32_bf16 v[52:55], v[150:153], v[166:169], v[52:55]
	v_mfma_f32_16x16x32_bf16 v[44:47], v[158:161], v[166:169], v[44:47]
	v_mfma_f32_16x16x32_bf16 v[36:39], v[150:153], v[174:177], v[36:39]
	v_mfma_f32_16x16x32_bf16 v[28:31], v[158:161], v[174:177], v[28:31]
	s_barrier
	v_mfma_f32_16x16x32_bf16 v[20:23], v[150:153], v[212:215], v[20:23]
	v_mfma_f32_16x16x32_bf16 v[12:15], v[158:161], v[212:215], v[12:15]
	v_mfma_f32_16x16x32_bf16 v[4:7], v[150:153], v[242:245], v[4:7]
	v_mfma_f32_16x16x32_bf16 v[0:3], v[158:161], v[242:245], v[0:3]
	s_add_i32 s96, 0, 0x18000
	s_add_i32 s97, 0, 0x1c000
	v_add_u32_e32 v142, s96, v193
	v_add_u32_e32 v158, s97, v193
	ds_read_b128 v[130:133], v142
	ds_read_b128 v[134:137], v142 offset:1024
	ds_read_b128 v[138:141], v142 offset:2048
	ds_read_b128 v[142:145], v142 offset:3072
	ds_read_b128 v[146:149], v158
	ds_read_b128 v[150:153], v158 offset:1024
	ds_read_b128 v[154:157], v158 offset:2048
	ds_read_b128 v[158:161], v158 offset:3072
	s_add_u32 s0, s0, s28
	s_addc_u32 s1, s1, 0
	s_mov_b32 m0, s9
	v_lshl_add_u64 v[250:251], s[0:1], 0, v[182:183]
	ds_read_b128 v[162:165], v207 offset:32768
	ds_read_b128 v[166:169], v207 offset:33792
	ds_read_b128 v[170:173], v207 offset:34816
	ds_read_b128 v[174:177], v207 offset:35840
	ds_read_b128 v[208:211], v207 offset:36864
	ds_read_b128 v[212:215], v207 offset:37888
	ds_read_b128 v[232:235], v207 offset:38912
	ds_read_b128 v[242:245], v207 offset:39936
	global_load_lds_dwordx4 v[250:251], off
	v_lshl_add_u64 v[250:251], s[0:1], 0, v[180:181]
	s_mov_b32 m0, s33
	s_nop 0
	global_load_lds_dwordx4 v[250:251], off
	s_waitcnt vmcnt(8)
	s_waitcnt lgkmcnt(0)
	s_barrier
	v_mfma_f32_16x16x32_bf16 v[126:129], v[130:133], v[162:165], v[126:129]
	v_mfma_f32_16x16x32_bf16 v[122:125], v[138:141], v[162:165], v[122:125]
	v_mfma_f32_16x16x32_bf16 v[114:117], v[130:133], v[170:173], v[114:117]
	v_mfma_f32_16x16x32_bf16 v[106:109], v[138:141], v[170:173], v[106:109]
	v_mfma_f32_16x16x32_bf16 v[98:101], v[130:133], v[208:211], v[98:101]
	v_mfma_f32_16x16x32_bf16 v[88:91], v[138:141], v[208:211], v[88:91]
	v_mfma_f32_16x16x32_bf16 v[80:83], v[130:133], v[232:235], v[80:83]
	v_mfma_f32_16x16x32_bf16 v[72:75], v[138:141], v[232:235], v[72:75]
	v_mfma_f32_16x16x32_bf16 v[126:129], v[134:137], v[166:169], v[126:129]
	v_mfma_f32_16x16x32_bf16 v[122:125], v[142:145], v[166:169], v[122:125]
	v_mfma_f32_16x16x32_bf16 v[114:117], v[134:137], v[174:177], v[114:117]
	v_mfma_f32_16x16x32_bf16 v[106:109], v[142:145], v[174:177], v[106:109]
	v_mfma_f32_16x16x32_bf16 v[98:101], v[134:137], v[212:215], v[98:101]
	v_mfma_f32_16x16x32_bf16 v[88:91], v[142:145], v[212:215], v[88:91]
	v_mfma_f32_16x16x32_bf16 v[80:83], v[134:137], v[242:245], v[80:83]
	v_mfma_f32_16x16x32_bf16 v[72:75], v[142:145], v[242:245], v[72:75]
	v_mfma_f32_16x16x32_bf16 v[118:121], v[146:149], v[162:165], v[118:121]
	v_mfma_f32_16x16x32_bf16 v[110:113], v[154:157], v[162:165], v[110:113]
	v_mfma_f32_16x16x32_bf16 v[102:105], v[146:149], v[170:173], v[102:105]
	v_mfma_f32_16x16x32_bf16 v[92:95], v[154:157], v[170:173], v[92:95]
	v_mfma_f32_16x16x32_bf16 v[84:87], v[146:149], v[208:211], v[84:87]
	v_mfma_f32_16x16x32_bf16 v[76:79], v[154:157], v[208:211], v[76:79]
	v_mfma_f32_16x16x32_bf16 v[68:71], v[146:149], v[232:235], v[68:71]
	v_mfma_f32_16x16x32_bf16 v[64:67], v[154:157], v[232:235], v[64:67]
	v_mfma_f32_16x16x32_bf16 v[118:121], v[150:153], v[166:169], v[118:121]
	v_mfma_f32_16x16x32_bf16 v[110:113], v[158:161], v[166:169], v[110:113]
	v_mfma_f32_16x16x32_bf16 v[102:105], v[150:153], v[174:177], v[102:105]
	v_mfma_f32_16x16x32_bf16 v[92:95], v[158:161], v[174:177], v[92:95]
	s_barrier
; #define PG8_STAGE(bufoff, gbase, voff) do { _Pragma("unroll") for (int _i = 0; _i < 2; ++_i) \
;         __builtin_amdgcn_global_load_lds((const unsigned*)((const char*)(gbase) + (voff)[_i]), (PG8_LAS unsigned*)(lds + (bufoff) + ldsw + _i * 8192), 16, 0, 0); } while (0)
; #define PG8_LDA(dst, b, h) do { _Pragma("unroll") for (int m = 0; m < 4; ++m) _Pragma("unroll") for (int k = 0; k < 2; ++k) dst[m][k] = *(const PG8_LAS bf16x8*)(lds + PG8_SA(b, h) + aoff + m * 2048 + k * 1024); } while (0)
; #define PG8_MMA(ai, bj, At, Bt) do { __builtin_amdgcn_s_setprio(1); _Pragma("unroll") for (int m = 0; m < 4; ++m) _Pragma("unroll") for (int n = 0; n < 2; ++n) _Pragma("unroll") for (int k = 0; k < 2; ++k) \
;         acc[ai][bj][m][n] = __builtin_amdgcn_mfma_f32_16x16x32_bf16(Bt[n][k], At[m][k], acc[ai][bj][m][n], 0, 0, 0); __builtin_amdgcn_s_setprio(0); } while (0)
; #define PG8_WAIT_V(n) asm volatile("s_waitcnt vmcnt(" #n ")" ::: "memory")
; #define PG8_WAIT_L(n) asm volatile("s_waitcnt lgkmcnt(" #n ")" ::: "memory")
; #define PG8_BAR __builtin_amdgcn_s_barrier()
; #define PG8_SCHED __builtin_amdgcn_sched_barrier(0)
; template <class Epi, class Sched, bool ALIGN_EPI = false, bool SP2 = false>
; __device__ __forceinline__ void gemm_phase(PG8_LAS unsigned char* lds, const Gemm g, const Sched& S, const Epi& E) {
;     ...
;             PG8_LDA(At, 1, 1); PG8_STAGE(PG8_SB(1, 0), b3, voffB); PG8_STAGE(PG8_SB(1, 1), b3 + hstep, voffB); PG8_STAGE(PG8_SA(1, 0), a3, voffA);
;             PG8_WAIT_V(8); PG8_WAIT_L(0); PG8_BAR; PG8_MMA(1, 0, At, B0); PG8_MMA(1, 1, At, B1); PG8_BAR; PG8_SCHED;
	v_mfma_f32_16x16x32_bf16 v[84:87], v[150:153], v[212:215], v[84:87]
	v_mfma_f32_16x16x32_bf16 v[76:79], v[158:161], v[212:215], v[76:79]
	v_mfma_f32_16x16x32_bf16 v[68:71], v[150:153], v[242:245], v[68:71]
	v_mfma_f32_16x16x32_bf16 v[64:67], v[158:161], v[242:245], v[64:67]
	s_add_i32 s0, s96, s4
	v_lshl_add_u64 v[202:203], v[202:203], 0, s[20:21]
	s_mov_b32 m0, s0
	ds_read_b128 v[162:165], v207 offset:49152
	ds_read_b128 v[166:169], v207 offset:50176
	ds_read_b128 v[170:173], v207 offset:51200
	ds_read_b128 v[174:177], v207 offset:52224
	ds_read_b128 v[208:211], v207 offset:53248
	ds_read_b128 v[212:215], v207 offset:54272
	ds_read_b128 v[232:235], v207 offset:55296
	ds_read_b128 v[242:245], v207 offset:56320
	global_load_lds_dwordx4 v[202:203], off
	v_lshl_add_u64 v[202:203], v[228:229], 0, s[20:21]
	s_add_i32 m0, s0, 0x2000
	s_add_i32 s0, s97, s4
	global_load_lds_dwordx4 v[202:203], off
	v_lshl_add_u64 v[202:203], v[230:231], 0, s[20:21]
	s_mov_b32 m0, s0
	s_nop 0
	global_load_lds_dwordx4 v[202:203], off
	v_lshl_add_u64 v[202:203], v[246:247], 0, s[20:21]
	s_add_i32 m0, s0, 0x2000
	s_nop 0
	global_load_lds_dwordx4 v[202:203], off
	v_lshl_add_u64 v[202:203], v[248:249], 0, s[20:21]
	s_mov_b32 m0, s53
	s_nop 0
	global_load_lds_dwordx4 v[202:203], off
	v_lshl_add_u64 v[202:203], v[236:237], 0, s[20:21]
	s_mov_b32 m0, s93
	s_nop 0
	global_load_lds_dwordx4 v[202:203], off
	s_waitcnt vmcnt(8)
	s_waitcnt lgkmcnt(0)
	s_barrier
	v_mfma_f32_16x16x32_bf16 v[60:63], v[130:133], v[162:165], v[60:63]
	v_mfma_f32_16x16x32_bf16 v[56:59], v[138:141], v[162:165], v[56:59]
	v_mfma_f32_16x16x32_bf16 v[48:51], v[130:133], v[170:173], v[48:51]
	v_mfma_f32_16x16x32_bf16 v[40:43], v[138:141], v[170:173], v[40:43]
	v_mfma_f32_16x16x32_bf16 v[32:35], v[130:133], v[208:211], v[32:35]
	v_mfma_f32_16x16x32_bf16 v[24:27], v[138:141], v[208:211], v[24:27]
	v_mfma_f32_16x16x32_bf16 v[16:19], v[130:133], v[232:235], v[16:19]
	v_mfma_f32_16x16x32_bf16 v[8:11], v[138:141], v[232:235], v[8:11]
	v_mfma_f32_16x16x32_bf16 v[60:63], v[134:137], v[166:169], v[60:63]
	v_mfma_f32_16x16x32_bf16 v[56:59], v[142:145], v[166:169], v[56:59]
	v_mfma_f32_16x16x32_bf16 v[48:51], v[134:137], v[174:177], v[48:51]
	v_mfma_f32_16x16x32_bf16 v[40:43], v[142:145], v[174:177], v[40:43]
	v_mfma_f32_16x16x32_bf16 v[32:35], v[134:137], v[212:215], v[32:35]
	v_mfma_f32_16x16x32_bf16 v[24:27], v[142:145], v[212:215], v[24:27]
	v_mfma_f32_16x16x32_bf16 v[16:19], v[134:137], v[242:245], v[16:19]
	v_mfma_f32_16x16x32_bf16 v[8:11], v[142:145], v[242:245], v[8:11]
	v_mfma_f32_16x16x32_bf16 v[52:55], v[146:149], v[162:165], v[52:55]
	v_mfma_f32_16x16x32_bf16 v[44:47], v[154:157], v[162:165], v[44:47]
	v_mfma_f32_16x16x32_bf16 v[36:39], v[146:149], v[170:173], v[36:39]
	v_mfma_f32_16x16x32_bf16 v[28:31], v[154:157], v[170:173], v[28:31]
	v_mfma_f32_16x16x32_bf16 v[20:23], v[146:149], v[208:211], v[20:23]
	v_mfma_f32_16x16x32_bf16 v[12:15], v[154:157], v[208:211], v[12:15]
	v_mfma_f32_16x16x32_bf16 v[4:7], v[146:149], v[232:235], v[4:7]
	v_mfma_f32_16x16x32_bf16 v[0:3], v[154:157], v[232:235], v[0:3]
	v_mfma_f32_16x16x32_bf16 v[52:55], v[150:153], v[166:169], v[52:55]
	v_mfma_f32_16x16x32_bf16 v[44:47], v[158:161], v[166:169], v[44:47]
	v_mfma_f32_16x16x32_bf16 v[36:39], v[150:153], v[174:177], v[36:39]
	v_mfma_f32_16x16x32_bf16 v[28:31], v[158:161], v[174:177], v[28:31]
	s_barrier
	v_mfma_f32_16x16x32_bf16 v[20:23], v[150:153], v[212:215], v[20:23]
	v_mfma_f32_16x16x32_bf16 v[12:15], v[158:161], v[212:215], v[12:15]
	v_mfma_f32_16x16x32_bf16 v[4:7], v[150:153], v[242:245], v[4:7]
	v_mfma_f32_16x16x32_bf16 v[0:3], v[158:161], v[242:245], v[0:3]
	s_add_u32 s45, s45, 0x100
	s_addc_u32 s94, s94, 0
	s_add_u32 s40, s40, 0x100
	s_addc_u32 s41, s41, 0
	s_cmp_ge_u32 s95, s58
	s_mov_b32 s0, s95
	s_cbranch_scc0 .LBB0_510
	s_and_b64 vcc, exec, s[82:83]
	s_cbranch_vccz .LBB0_513
	s_barrier
